# rwprep: next-tile prefetch (one cache-warming load per thread on the next token tile's projection / v_first lines, issued after the stage-2 barrier)
# baseline (speedup 1.0000x reference)
;     __device__ __forceinline__ const float* in(int i) const { return (const float*)(const __attribute__((address_space(1))) float*)ld(i); }
; __device__ __forceinline__ void lds_barrier() { asm volatile("s_waitcnt lgkmcnt(0)" ::: "memory"); __builtin_amdgcn_s_barrier(); asm volatile("" ::: "memory"); }
; __device__ __forceinline__ void phase_rwprep(const Params& p, int l, LAS unsigned char* lds, int tid, int lane, int wave) {
;     ...
;         lds_barrier();
;         if (tid < RWW) {
;             const int c = tid, h = tid >> 6;
;             const float w0c = p.in(9)[l * RWW + c], a0c = p.in(11)[l * RWW + c];
;             const float v0c = l > 0 ? p.in(21)[lv * RWW + c] : 0.f;
;             const float mur = mu[c], muk = mu[384 + c], muv = mu[768 + c];
;             const float kkc = p.in(14)[l * RWW + c], kac = p.in(15)[l * RWW + c], rkc = p.in(16)[l * RWW + c];
;             bf16_t rr_[17], kr_[17], vr_[17], vf_[16];
; #pragma unroll
;             for (int t = 0; t < 17; ++t) {
;                 const int tok = t0 - 1 + t;
;                 if (tok >= 0) { const bf16_t* qq = PR + (size_t)tok * PRW + c; rr_[t] = qq[0]; kr_[t] = qq[384]; vr_[t] = qq[768]; }
.LBB0_895:
	s_nop 6
	ds_write_b32 v183, v22 offset:49152
	ds_write_b32 v184, v14
	ds_write2st64_b32 v151, v10, v11 offset0:68 offset1:74
	ds_write2st64_b32 v151, v6, v7 offset0:164 offset1:170
	ds_write_b32 v185, v23 offset:49152
	ds_write_b32 v186, v15
	ds_write_b32 v187, v24 offset:49152
	ds_write_b32 v188, v16
	ds_write2st64_b32 v151, v12, v13 offset0:80 offset1:86
	ds_write2st64_b32 v151, v8, v9 offset0:176 offset1:182
	ds_write_b32 v189, v25 offset:49152
	ds_write_b32 v190, v17
	s_waitcnt lgkmcnt(0)
	s_barrier
	s_cmpk_gt_i32 s2, 0x2ff
	s_cbranch_scc1 .Lmy_rwp_nopf
	s_add_i32 s10, s72, 0x1001
	v_lshrrev_b32_e32 v36, 5, v130
	v_and_b32_e32 v38, 31, v130
	v_add_u32_e32 v36, s10, v36
	v_cmp_lt_u32_e32 vcc, 23, v38
	v_mov_b32_e32 v40, 0x300
	v_subrev_u32_e32 v41, 24, v38
	v_mov_b32_e32 v44, 0x6b80000
	v_mov_b32_e32 v39, 0xc00
	v_cndmask_b32_e32 v41, v38, v41, vcc
	v_cndmask_b32_e32 v40, v39, v40, vcc
	v_mov_b32_e32 v39, 0xef80000
	s_nop 0
	v_cndmask_b32_e32 v44, v39, v44, vcc
	v_mul_u32_u24_e32 v36, v36, v40
	v_lshl_add_u32 v36, v41, 7, v36
	v_add_u32_e32 v36, v36, v44
	global_load_dword v36, v36, s[92:93]
.Lmy_rwp_nopf:
	s_and_saveexec_b64 s[62:63], s[4:5]
	s_cbranch_execz .LBB0_744
	v_readlane_b32 s10, v254, 35
	v_mov_b32_e32 v34, 0
	s_and_b64 vcc, exec, s[64:65]
	s_waitcnt lgkmcnt(14)
	v_mov_b32_e32 v2, s10
	ds_read_b64 v[2:3], v2
	v_mov_b32_e32 v43, 0
	s_waitcnt lgkmcnt(0)
	v_readfirstlane_b32 s10, v2
	v_readfirstlane_b32 s11, v3
	s_nop 1
	v_lshl_add_u64 v[2:3], s[10:11], 0, v[128:129]
	v_readlane_b32 s10, v254, 36
	global_load_dword v36, v[2:3], off
	s_nop 0
	v_mov_b32_e32 v2, s10
	ds_read_b64 v[2:3], v2
	s_waitcnt lgkmcnt(0)
	v_readfirstlane_b32 s10, v2
	v_readfirstlane_b32 s11, v3
	s_nop 1
	v_lshl_add_u64 v[2:3], s[10:11], 0, v[128:129]
	global_load_dword v38, v[2:3], off
	s_cbranch_vccnz .LBB0_898
	v_readlane_b32 s10, v254, 37
	s_nop 1
	v_mov_b32_e32 v2, s10
	ds_read_b64 v[2:3], v2
	s_waitcnt lgkmcnt(0)
	v_readfirstlane_b32 s10, v2
	v_readfirstlane_b32 s11, v3
	s_nop 0
	v_mov_b32_e32 v2, s10
	v_mov_b32_e32 v3, s11
	v_lshl_add_u64 v[2:3], v[56:57], 2, v[2:3]
	global_load_dword v43, v[2:3], off
